# LayerNorm loops: adaLN scale/shift reloaded only when the batch index changes (fewer L2 bytes per row)
# speedup vs baseline: 1.0051x; 1.0051x over previous
; DI int tidx() { int t = __builtin_amdgcn_workitem_id_x(); asm volatile("" : "+v"(t)); return t; }
; DI void phase_ln(const Params& p, const float* g, const float* bta, const float* sh, const float* sc, bool writex, int bid, int nb) {
;   const int tid = tidx(), lane = tid & 63, wid = tid >> 6;
;   for (int row = bid * 8 + wid; row < NTOK; row += nb * 8) {
;     float* xr = p.out + (size_t)row * DM; const int b = row >> 12;
;     f32x4 v[4]; float s = 0.f;
; #pragma unroll
;     for (int e = 0; e < 4; ++e) { v[e] = *(const f32x4*)(xr + e * 256 + lane * 4); s += (v[e][0] + v[e][1]) + (v[e][2] + v[e][3]); }
; #pragma unroll
;     for (int o = 32; o > 0; o >>= 1) s += __shfl_xor(s, o);
;     const float mu = s * (1.f / 1024.f); float q = 0.f;
; #pragma unroll
;     for (int e = 0; e < 4; ++e) { v[e] -= mu; q += (v[e][0] * v[e][0] + v[e][1] * v[e][1]) + (v[e][2] * v[e][2] + v[e][3] * v[e][3]); }
; #pragma unroll
;     for (int o = 32; o > 0; o >>= 1) q += __shfl_xor(q, o);
;     const float rstd = rsqrtf(q * (1.f / 1024.f) + 1e-5f);
;     if (!writex && lane == 0) { f32x2 ms = {mu, rstd}; *(f32x2*)(p.lnstat + (size_t)row * 2) = ms; }
.LBB0_779:
	s_or_b64 exec, exec, s[0:1]
	s_lshl_b32 s4, s79, 3
	v_mov_b32_e32 v1, v206
	s_mov_b32 s0, s4
	s_waitcnt lgkmcnt(0)
	s_barrier
	v_writelane_b32 v255, s0, 3
	v_ashrrev_i32_e32 v0, 6, v1
	v_add_u32_e32 v31, s4, v0
	v_writelane_b32 v255, s1, 4
	s_mov_b32 s0, 0x8000
	v_cmp_gt_i32_e32 vcc, s0, v31
	s_and_saveexec_b64 s[4:5], vcc
	s_cbranch_execz .LBB0_784
	v_cmp_lt_i32_e64 s[0:1], v209, v208
	v_and_b32_e32 v6, 63, v1
	v_readlane_b32 s8, v252, 60
	v_cndmask_b32_e64 v1, v207, v209, s[0:1]
	v_lshlrev_b32_e32 v32, 2, v1
	v_xor_b32_e32 v1, 16, v207
	v_cmp_lt_i32_e64 s[0:1], v1, v208
	v_readlane_b32 s9, v252, 61
	v_readlane_b32 s10, v252, 62
	v_cndmask_b32_e64 v1, v207, v1, s[0:1]
	v_lshlrev_b32_e32 v33, 2, v1
	v_xor_b32_e32 v1, 8, v207
	v_cmp_lt_i32_e64 s[0:1], v1, v208
	v_readlane_b32 s11, v252, 63
	v_readlane_b32 s12, v251, 0
	v_cndmask_b32_e64 v1, v207, v1, s[0:1]
	v_lshlrev_b32_e32 v34, 2, v1
	v_xor_b32_e32 v1, 4, v207
	v_cmp_lt_i32_e64 s[0:1], v1, v208
	v_readlane_b32 s13, v251, 1
	v_readlane_b32 s14, v251, 2
	v_cndmask_b32_e64 v1, v207, v1, s[0:1]
	v_lshlrev_b32_e32 v35, 2, v1
	v_xor_b32_e32 v1, 2, v207
	v_readlane_b32 s15, v251, 3
	v_readlane_b32 s16, v251, 4
	v_readlane_b32 s17, v251, 5
	v_cmp_lt_i32_e64 s[0:1], v1, v208
	v_readlane_b32 s18, v251, 6
	v_readlane_b32 s19, v251, 7
	v_readlane_b32 s20, v251, 8
	v_readlane_b32 s21, v251, 9
	v_readlane_b32 s22, v251, 10
	v_readlane_b32 s23, v251, 11
	s_mov_b64 s[8:9], s[16:17]
	v_cndmask_b32_e64 v1, v207, v1, s[0:1]
	v_lshlrev_b32_e32 v2, 4, v6
	v_mov_b32_e32 v3, 0
	s_mov_b64 s[10:11], s[18:19]
	s_mov_b64 s[12:13], s[20:21]
	s_mov_b64 s[14:15], s[22:23]
	v_lshlrev_b32_e32 v36, 2, v1
	v_xor_b32_e32 v1, 1, v207
	v_lshl_add_u64 v[16:17], s[12:13], 0, v[2:3]
	v_lshl_add_u64 v[18:19], s[14:15], 0, v[2:3]
	v_readlane_b32 s8, v252, 17
	v_cmp_lt_i32_e64 s[0:1], v1, v208
	v_readlane_b32 s16, v252, 25
	v_readlane_b32 s17, v252, 26
	v_cndmask_b32_e64 v1, v207, v1, s[0:1]
	s_mov_b64 s[0:1], 0x4000
	v_lshl_add_u64 v[4:5], s[16:17], 0, v[2:3]
	v_lshl_add_u64 v[20:21], v[4:5], 0, s[0:1]
	s_mov_b64 s[0:1], 0x3000
	v_readlane_b32 s9, v252, 18
	v_lshl_add_u64 v[22:23], v[4:5], 0, s[0:1]
	v_readlane_b32 s0, v255, 3
	v_lshlrev_b32_e32 v37, 2, v1
	v_readlane_b32 s10, v252, 19
	v_readlane_b32 s11, v252, 20
	v_readlane_b32 s12, v252, 21
	v_readlane_b32 s13, v252, 22
	v_readlane_b32 s14, v252, 23
	v_readlane_b32 s15, v252, 24
	v_readlane_b32 s18, v252, 27
	v_readlane_b32 s19, v252, 28
	v_readlane_b32 s20, v252, 29
	v_readlane_b32 s21, v252, 30
	v_readlane_b32 s22, v252, 31
	v_readlane_b32 s23, v252, 32
	v_ashrrev_i32_e32 v1, 31, v0
	s_mov_b32 s8, s0
	s_ashr_i32 s9, s0, 31
	v_lshl_add_u64 v[0:1], v[0:1], 0, s[8:9]
	v_readlane_b32 s8, v252, 0
	v_readlane_b32 s1, v255, 4
	v_readlane_b32 s9, v252, 1
	v_lshlrev_b64 v[4:5], 12, v[0:1]
	v_writelane_b32 v255, s0, 3
	v_lshl_add_u64 v[24:25], v[0:1], 3, s[8:9]
	v_or_b32_e32 v4, v4, v2
	v_lshlrev_b64 v[0:1], 11, v[0:1]
	s_lshl_b32 s6, s38, 3
	v_writelane_b32 v255, s1, 4
	v_readlane_b32 s14, v252, 6
	v_readlane_b32 s15, v252, 7
	v_lshl_add_u64 v[2:3], s[84:85], 0, v[4:5]
	s_mov_b64 s[0:1], 0x800
	v_lshl_or_b32 v0, v6, 3, v0
	v_readlane_b32 s10, v252, 2
	v_readlane_b32 s11, v252, 3
	v_readlane_b32 s12, v252, 4
	v_readlane_b32 s13, v252, 5
	s_ashr_i32 s7, s6, 31
	v_lshl_add_u64 v[26:27], v[2:3], 0, s[0:1]
	v_lshl_add_u64 v[0:1], s[14:15], 0, v[0:1]
	s_mov_b64 s[0:1], 0x400
	v_cmp_eq_u32_e32 vcc, 0, v6
	s_lshl_b64 s[8:9], s[6:7], 3
	s_lshl_b64 s[10:11], s[6:7], 12
	v_lshl_add_u64 v[28:29], v[0:1], 0, s[0:1]
	s_lshl_b64 s[12:13], s[6:7], 11
	s_mov_b64 s[14:15], 0
	v_mov_b32_e32 v38, 0x3727c5ac
	v_readlane_b32 s16, v252, 8
	v_readlane_b32 s17, v252, 9
	v_readlane_b32 s18, v252, 10
	v_readlane_b32 s19, v252, 11
	v_readlane_b32 s20, v252, 12
	v_readlane_b32 s21, v252, 13
	v_readlane_b32 s22, v252, 14
	v_readlane_b32 s23, v252, 15
	global_load_dwordx4 v[52:55], v[16:17], off
	global_load_dwordx4 v[68:71], v[18:19], off
	global_load_dwordx4 v[56:59], v[16:17], off offset:1024
	global_load_dwordx4 v[72:75], v[18:19], off offset:1024
	global_load_dwordx4 v[60:63], v[16:17], off offset:2048
	global_load_dwordx4 v[76:79], v[18:19], off offset:2048
	global_load_dwordx4 v[64:67], v[16:17], off offset:3072
	global_load_dwordx4 v[80:83], v[18:19], off offset:3072
	s_mov_b32 s101, -1
	global_load_dwordx4 v[124:127], v[26:27], off offset:-2048
	global_load_dwordx4 v[128:131], v[26:27], off offset:-1024
	global_load_dwordx4 v[132:135], v[26:27], off
	global_load_dwordx4 v[136:139], v[26:27], off offset:1024
	s_waitcnt vmcnt(0)
	s_branch .LBB0_782

; DI void st4(bf16_t* p, float a, float b, float c, float d) { u32x2 w = {pk2(a, b), pk2(c, d)}; *(u32x2*)p = w; }
; DI void phase_ln(const Params& p, const float* g, const float* bta, const float* sh, const float* sc, bool writex, int bid, int nb) {
;     ...
;   for (int row = bid * 8 + wid; row < NTOK; row += nb * 8) {
;     float* xr = p.out + (size_t)row * DM; const int b = row >> 12;
;     f32x4 v[4]; float s = 0.f;
; #pragma unroll
;     for (int e = 0; e < 4; ++e) { v[e] = *(const f32x4*)(xr + e * 256 + lane * 4); s += (v[e][0] + v[e][1]) + (v[e][2] + v[e][3]); }
; #pragma unroll
;     for (int o = 32; o > 0; o >>= 1) s += __shfl_xor(s, o);
;     const float mu = s * (1.f / 1024.f); float q = 0.f;
; #pragma unroll
;     for (int e = 0; e < 4; ++e) { v[e] -= mu; q += (v[e][0] * v[e][0] + v[e][1] * v[e][1]) + (v[e][2] * v[e][2] + v[e][3] * v[e][3]); }
; #pragma unroll
;     for (int o = 32; o > 0; o >>= 1) q += __shfl_xor(q, o);
;     const float rstd = rsqrtf(q * (1.f / 1024.f) + 1e-5f);
;     if (!writex && lane == 0) { f32x2 ms = {mu, rstd}; *(f32x2*)(p.lnstat + (size_t)row * 2) = ms; }
; #pragma unroll
;     for (int e = 0; e < 4; ++e) { const int col = e * 256 + lane * 4;
;       const f32x4 y = v[e] * rstd * *(const f32x4*)(g + col) + *(const f32x4*)(bta + col);
;       if (writex) *(f32x4*)(xr + col) = y;
;       if (sh) { const f32x4 hv = y * (*(const f32x4*)(sc + b * 6144 + col) + 1.f) + *(const f32x4*)(sh + b * 6144 + col); st4(p.H + (size_t)row * DM + col, hv[0], hv[1], hv[2], hv[3]); } }
.LBB0_782:
	s_waitcnt vmcnt(5)
	v_ashrrev_i32_e32 v116, 12, v31
	v_mov_b64_e32 v[12:13], v[124:125]
	v_mov_b64_e32 v[14:15], v[126:127]
	v_mov_b64_e32 v[8:9], v[128:129]
	v_mov_b64_e32 v[10:11], v[130:131]
	v_mov_b64_e32 v[4:5], v[132:133]
	v_mov_b64_e32 v[6:7], v[134:135]
	v_mov_b64_e32 v[0:1], v[136:137]
	v_mov_b64_e32 v[2:3], v[138:139]
	v_readfirstlane_b32 s100, v116
	s_nop 3
	s_cmp_eq_u32 s100, s101
	s_cbranch_scc1 .Lln_skip_a
	s_mov_b32 s101, s100
	v_mul_i32_i24_e32 v116, 0x1800, v116
	v_ashrrev_i32_e32 v117, 31, v116
	v_lshlrev_b64 v[116:117], 2, v[116:117]
	v_lshl_add_u64 v[118:119], v[20:21], 0, v[116:117]
	v_lshl_add_u64 v[116:117], v[22:23], 0, v[116:117]
	global_load_dwordx4 v[84:87], v[118:119], off
	global_load_dwordx4 v[100:103], v[116:117], off
	global_load_dwordx4 v[88:91], v[118:119], off offset:1024
	global_load_dwordx4 v[104:107], v[116:117], off offset:1024
	global_load_dwordx4 v[92:95], v[118:119], off offset:2048
	global_load_dwordx4 v[108:111], v[116:117], off offset:2048
	global_load_dwordx4 v[96:99], v[118:119], off offset:3072
	global_load_dwordx4 v[112:115], v[116:117], off offset:3072
.Lln_skip_a:
	v_add_u32_e32 v140, s6, v31
	s_movk_i32 s100, 0x7fff
	v_cmp_ge_i32_e64 s[98:99], s100, v140
	v_lshl_add_u64 v[142:143], v[26:27], 0, s[10:11]
	s_nop 1
	v_cndmask_b32_e64 v142, v26, v142, s[98:99]
	v_cndmask_b32_e64 v143, v27, v143, s[98:99]
	global_load_dwordx4 v[124:127], v[142:143], off offset:-2048
	global_load_dwordx4 v[128:131], v[142:143], off offset:-1024
	global_load_dwordx4 v[132:135], v[142:143], off
	global_load_dwordx4 v[136:139], v[142:143], off offset:1024
	s_mov_b32 s0, 0x800000
	v_mov_b32_e32 v120, v13
	v_mov_b32_e32 v121, v14
	v_mov_b32_e32 v122, v12
	v_mov_b32_e32 v123, v15
	v_pk_add_f32 v[120:121], v[120:121], v[122:123]
	v_mov_b32_e32 v122, v8
	v_add_f32_e32 v120, v120, v121
	v_add_f32_e32 v40, 0, v120
	v_mov_b32_e32 v120, v9
	v_mov_b32_e32 v121, v10
	v_mov_b32_e32 v123, v11
	v_pk_add_f32 v[120:121], v[120:121], v[122:123]
	s_nop 0
	v_pk_add_f32 v[42:43], v[120:121], v[120:121] op_sel:[0,1] op_sel_hi:[1,0]
	v_add_f32_e32 v44, v4, v5
	v_add_f32_e32 v46, v6, v7
	v_mov_b32_e32 v41, v0
	v_mov_b32_e32 v43, v1
	v_mov_b32_e32 v45, v2
	v_mov_b32_e32 v47, v3
	v_pk_add_f32 v[40:41], v[40:41], v[42:43]
	v_pk_add_f32 v[42:43], v[44:45], v[46:47]
	s_nop 0
	v_pk_add_f32 v[40:41], v[40:41], v[42:43]
	s_nop 0
	v_add_f32_e32 v30, v40, v41
	ds_bpermute_b32 v39, v32, v30
	s_waitcnt lgkmcnt(0)
	v_add_f32_e32 v30, v30, v39
	ds_bpermute_b32 v39, v33, v30
	s_waitcnt lgkmcnt(0)
	v_add_f32_e32 v30, v30, v39
	ds_bpermute_b32 v39, v34, v30
	s_waitcnt lgkmcnt(0)
	v_add_f32_e32 v30, v30, v39
	ds_bpermute_b32 v39, v35, v30
	s_waitcnt lgkmcnt(0)
	v_add_f32_e32 v30, v30, v39
	ds_bpermute_b32 v39, v36, v30
	s_waitcnt lgkmcnt(0)
	v_add_f32_e32 v30, v30, v39
	ds_bpermute_b32 v39, v37, v30
	s_waitcnt lgkmcnt(0)
	v_add_f32_e32 v39, v30, v39
	v_fmamk_f32 v15, v39, 0xba800000, v15
	v_fmamk_f32 v14, v39, 0xba800000, v14
	v_fmamk_f32 v13, v39, 0xba800000, v13
	v_fmac_f32_e32 v12, 0xba800000, v39
	v_pk_mul_f32 v[40:41], v[14:15], v[14:15]
	v_pk_mul_f32 v[42:43], v[12:13], v[12:13]
	v_fmamk_f32 v11, v39, 0xba800000, v11
	v_pk_mov_b32 v[44:45], v[42:43], v[40:41] op_sel:[1,0]
	v_mov_b32_e32 v43, v41
	v_fmamk_f32 v10, v39, 0xba800000, v10
	v_fmamk_f32 v9, v39, 0xba800000, v9
	v_fmac_f32_e32 v8, 0xba800000, v39
	v_pk_add_f32 v[40:41], v[44:45], v[42:43]
	v_pk_mul_f32 v[42:43], v[10:11], v[10:11]
	v_pk_mul_f32 v[44:45], v[8:9], v[8:9]
	v_fmac_f32_e32 v4, 0xba800000, v39
	v_pk_mov_b32 v[46:47], v[44:45], v[42:43] op_sel:[1,0]
	v_mov_b32_e32 v45, v43
	v_fmamk_f32 v6, v39, 0xba800000, v6
	v_fmamk_f32 v5, v39, 0xba800000, v5
	v_mul_f32_e32 v30, v4, v4
	v_pk_add_f32 v[42:43], v[46:47], v[44:45]
	v_fmamk_f32 v7, v39, 0xba800000, v7
	v_pk_fma_f32 v[44:45], v[4:5], v[4:5], v[30:31] op_sel_hi:[1,1,0]
	v_mul_f32_e32 v30, v6, v6
	v_pk_add_f32 v[40:41], v[40:41], v[40:41] op_sel_hi:[0,1]
	v_pk_add_f32 v[42:43], v[42:43], v[42:43] op_sel_hi:[0,1]
	v_pk_fma_f32 v[46:47], v[6:7], v[6:7], v[30:31] op_sel_hi:[1,1,0]
	v_fmamk_f32 v3, v39, 0xba800000, v3
	v_fmamk_f32 v2, v39, 0xba800000, v2
	v_fmamk_f32 v1, v39, 0xba800000, v1
	v_fmac_f32_e32 v0, 0xba800000, v39
	v_mul_f32_e32 v44, v0, v0
	v_mul_f32_e32 v46, v1, v1
	v_mul_f32_e32 v40, v2, v2
	v_mul_f32_e32 v42, v3, v3
	v_pk_add_f32 v[44:45], v[44:45], v[46:47]
	v_pk_add_f32 v[40:41], v[40:41], v[42:43]
	s_nop 0
	v_pk_add_f32 v[40:41], v[44:45], v[40:41]
	s_nop 0
	v_add_f32_e32 v30, v40, v41
	ds_bpermute_b32 v40, v32, v30
	s_waitcnt lgkmcnt(0)
	v_add_f32_e32 v30, v30, v40
	ds_bpermute_b32 v40, v33, v30
	s_waitcnt lgkmcnt(0)
	v_add_f32_e32 v30, v30, v40
	ds_bpermute_b32 v40, v34, v30
	s_waitcnt lgkmcnt(0)
	v_add_f32_e32 v30, v30, v40
	ds_bpermute_b32 v40, v35, v30
	s_waitcnt lgkmcnt(0)
	v_add_f32_e32 v30, v30, v40
	ds_bpermute_b32 v40, v36, v30
	s_waitcnt lgkmcnt(0)
	v_add_f32_e32 v30, v30, v40
	ds_bpermute_b32 v40, v37, v30
	s_waitcnt lgkmcnt(0)
	v_add_f32_e32 v30, v30, v40
	v_fmamk_f32 v30, v30, 0x3a800000, v38
	v_cmp_gt_f32_e64 s[0:1], s0, v30
	v_mul_f32_e32 v40, 0x4b800000, v30
	s_nop 0
	v_cndmask_b32_e64 v30, v30, v40, s[0:1]
	v_rsq_f32_e32 v30, v30
	s_nop 0
	v_mul_f32_e32 v40, 0x45800000, v30
	v_cndmask_b32_e64 v30, v30, v40, s[0:1]
	s_and_saveexec_b64 s[0:1], vcc
	s_cbranch_execz .LBB0_781
	v_mul_f32_e32 v40, 0x3a800000, v39
	v_mov_b32_e32 v41, v30
	global_store_dwordx2 v[24:25], v[40:41], off
	s_branch .LBB0_781

; DI int tidx() { int t = __builtin_amdgcn_workitem_id_x(); asm volatile("" : "+v"(t)); return t; }
; DI void phase_ln(const Params& p, const float* g, const float* bta, const float* sh, const float* sc, bool writex, int bid, int nb) {
;   const int tid = tidx(), lane = tid & 63, wid = tid >> 6;
;   for (int row = bid * 8 + wid; row < NTOK; row += nb * 8) {
;     float* xr = p.out + (size_t)row * DM; const int b = row >> 12;
;     f32x4 v[4]; float s = 0.f;
; #pragma unroll
;     for (int e = 0; e < 4; ++e) { v[e] = *(const f32x4*)(xr + e * 256 + lane * 4); s += (v[e][0] + v[e][1]) + (v[e][2] + v[e][3]); }
; #pragma unroll
;     for (int o = 32; o > 0; o >>= 1) s += __shfl_xor(s, o);
;     const float mu = s * (1.f / 1024.f); float q = 0.f;
; #pragma unroll
;     for (int e = 0; e < 4; ++e) { v[e] -= mu; q += (v[e][0] * v[e][0] + v[e][1] * v[e][1]) + (v[e][2] * v[e][2] + v[e][3] * v[e][3]); }
; #pragma unroll
;     for (int o = 32; o > 0; o >>= 1) q += __shfl_xor(q, o);
;     const float rstd = rsqrtf(q * (1.f / 1024.f) + 1e-5f);
;     if (!writex && lane == 0) { f32x2 ms = {mu, rstd}; *(f32x2*)(p.lnstat + (size_t)row * 2) = ms; }
.LBB0_1070:
	v_mov_b32_e32 v1, v206
	v_readlane_b32 s0, v255, 3
	v_ashrrev_i32_e32 v0, 6, v1
	v_readlane_b32 s1, v255, 4
	v_add_u32_e32 v31, s0, v0
	s_mov_b32 s0, 0x8000
	v_cmp_gt_i32_e32 vcc, s0, v31
	s_and_saveexec_b64 s[2:3], vcc
	s_cbranch_execz .LBB0_1075
	v_cmp_lt_i32_e64 s[0:1], v209, v208
	v_and_b32_e32 v6, 63, v1
	v_readlane_b32 s8, v252, 17
	v_cndmask_b32_e64 v1, v207, v209, s[0:1]
	v_lshlrev_b32_e32 v32, 2, v1
	v_xor_b32_e32 v1, 16, v207
	v_cmp_lt_i32_e64 s[0:1], v1, v208
	v_lshlrev_b32_e32 v2, 4, v6
	v_mov_b32_e32 v3, 0
	v_cndmask_b32_e64 v1, v207, v1, s[0:1]
	v_lshlrev_b32_e32 v33, 2, v1
	v_xor_b32_e32 v1, 8, v207
	v_cmp_lt_i32_e64 s[0:1], v1, v208
	v_readlane_b32 s16, v252, 25
	v_readlane_b32 s17, v252, 26
	v_cndmask_b32_e64 v1, v207, v1, s[0:1]
	v_lshlrev_b32_e32 v34, 2, v1
	v_xor_b32_e32 v1, 4, v207
	v_cmp_lt_i32_e64 s[0:1], v1, v208
	v_lshl_add_u64 v[4:5], s[16:17], 0, v[2:3]
	v_readlane_b32 s9, v252, 18
	v_cndmask_b32_e64 v1, v207, v1, s[0:1]
	v_lshlrev_b32_e32 v35, 2, v1
	v_xor_b32_e32 v1, 2, v207
	v_cmp_lt_i32_e64 s[0:1], v1, v208
	v_readlane_b32 s10, v252, 19
	v_readlane_b32 s11, v252, 20
	v_cndmask_b32_e64 v1, v207, v1, s[0:1]
	v_lshlrev_b32_e32 v36, 2, v1
	v_xor_b32_e32 v1, 1, v207
	v_cmp_lt_i32_e64 s[0:1], v1, v208
	v_readlane_b32 s12, v252, 21
	v_readlane_b32 s13, v252, 22
	v_cndmask_b32_e64 v1, v207, v1, s[0:1]
	s_mov_b64 s[0:1], 0x31000
	v_lshl_add_u64 v[20:21], v[4:5], 0, s[0:1]
	s_mov_b64 s[0:1], 0x30000
	v_lshl_add_u64 v[22:23], v[4:5], 0, s[0:1]
	v_readlane_b32 s0, v255, 3
	v_lshlrev_b32_e32 v37, 2, v1
	v_readlane_b32 s14, v252, 23
	v_readlane_b32 s15, v252, 24
	v_readlane_b32 s18, v252, 27
	v_readlane_b32 s19, v252, 28
	v_readlane_b32 s20, v252, 29
	v_readlane_b32 s21, v252, 30
	v_readlane_b32 s22, v252, 31
	v_readlane_b32 s23, v252, 32
	v_ashrrev_i32_e32 v1, 31, v0
	s_mov_b32 s6, s0
	s_ashr_i32 s7, s0, 31
	v_lshl_add_u64 v[0:1], v[0:1], 0, s[6:7]
	v_readlane_b32 s8, v252, 0
	v_readlane_b32 s1, v255, 4
	v_readlane_b32 s9, v252, 1
	v_lshlrev_b64 v[4:5], 12, v[0:1]
	v_writelane_b32 v255, s0, 3
	v_lshl_add_u64 v[24:25], v[0:1], 3, s[8:9]
	v_or_b32_e32 v4, v4, v2
	v_lshlrev_b64 v[0:1], 11, v[0:1]
	s_lshl_b32 s4, s38, 3
	v_lshl_add_u64 v[16:17], s[80:81], 0, v[2:3]
	v_lshl_add_u64 v[18:19], s[82:83], 0, v[2:3]
	v_writelane_b32 v255, s1, 4
	v_readlane_b32 s14, v252, 6
	v_readlane_b32 s15, v252, 7
	v_lshl_add_u64 v[2:3], s[84:85], 0, v[4:5]
	s_mov_b64 s[0:1], 0x800
	v_lshl_or_b32 v0, v6, 3, v0
	v_readlane_b32 s10, v252, 2
	v_readlane_b32 s11, v252, 3
	v_readlane_b32 s12, v252, 4
	v_readlane_b32 s13, v252, 5
	s_ashr_i32 s5, s4, 31
	v_lshl_add_u64 v[26:27], v[2:3], 0, s[0:1]
	v_lshl_add_u64 v[0:1], s[14:15], 0, v[0:1]
	s_mov_b64 s[0:1], 0x400
	v_cmp_eq_u32_e32 vcc, 0, v6
	s_lshl_b64 s[6:7], s[4:5], 3
	s_lshl_b64 s[8:9], s[4:5], 12
	v_lshl_add_u64 v[28:29], v[0:1], 0, s[0:1]
	s_lshl_b64 s[10:11], s[4:5], 11
	s_mov_b64 s[12:13], 0
	v_mov_b32_e32 v38, 0x3727c5ac
	v_readlane_b32 s16, v252, 8
	v_readlane_b32 s17, v252, 9
	v_readlane_b32 s18, v252, 10
	v_readlane_b32 s19, v252, 11
	v_readlane_b32 s20, v252, 12
	v_readlane_b32 s21, v252, 13
	v_readlane_b32 s22, v252, 14
	v_readlane_b32 s23, v252, 15
	global_load_dwordx4 v[52:55], v[16:17], off
	global_load_dwordx4 v[68:71], v[18:19], off
	global_load_dwordx4 v[56:59], v[16:17], off offset:1024
	global_load_dwordx4 v[72:75], v[18:19], off offset:1024
	global_load_dwordx4 v[60:63], v[16:17], off offset:2048
	global_load_dwordx4 v[76:79], v[18:19], off offset:2048
	global_load_dwordx4 v[64:67], v[16:17], off offset:3072
	global_load_dwordx4 v[80:83], v[18:19], off offset:3072
	s_mov_b32 s101, -1
	global_load_dwordx4 v[124:127], v[26:27], off offset:-2048
	global_load_dwordx4 v[128:131], v[26:27], off offset:-1024
	global_load_dwordx4 v[132:135], v[26:27], off
	global_load_dwordx4 v[136:139], v[26:27], off offset:1024
	s_waitcnt vmcnt(0)
	s_branch .LBB0_1073

; DI void phase_ln(const Params& p, const float* g, const float* bta, const float* sh, const float* sc, bool writex, int bid, int nb) {
;     ...
;   for (int row = bid * 8 + wid; row < NTOK; row += nb * 8) {
;     float* xr = p.out + (size_t)row * DM; const int b = row >> 12;
;     f32x4 v[4]; float s = 0.f;
; #pragma unroll
;     for (int e = 0; e < 4; ++e) { v[e] = *(const f32x4*)(xr + e * 256 + lane * 4); s += (v[e][0] + v[e][1]) + (v[e][2] + v[e][3]); }
; #pragma unroll
;     for (int o = 32; o > 0; o >>= 1) s += __shfl_xor(s, o);
;     const float mu = s * (1.f / 1024.f); float q = 0.f;
; #pragma unroll
;     for (int e = 0; e < 4; ++e) { v[e] -= mu; q += (v[e][0] * v[e][0] + v[e][1] * v[e][1]) + (v[e][2] * v[e][2] + v[e][3] * v[e][3]); }
; #pragma unroll
;     for (int o = 32; o > 0; o >>= 1) q += __shfl_xor(q, o);
;     const float rstd = rsqrtf(q * (1.f / 1024.f) + 1e-5f);
;     if (!writex && lane == 0) { f32x2 ms = {mu, rstd}; *(f32x2*)(p.lnstat + (size_t)row * 2) = ms; }
.Lln_skip_b:
	v_add_u32_e32 v140, s4, v31
	s_movk_i32 s100, 0x7fff
	v_cmp_ge_i32_e64 s[98:99], s100, v140
	v_lshl_add_u64 v[142:143], v[26:27], 0, s[8:9]
	s_nop 1
	v_cndmask_b32_e64 v142, v26, v142, s[98:99]
	v_cndmask_b32_e64 v143, v27, v143, s[98:99]
	global_load_dwordx4 v[124:127], v[142:143], off offset:-2048
	global_load_dwordx4 v[128:131], v[142:143], off offset:-1024
	global_load_dwordx4 v[132:135], v[142:143], off
	global_load_dwordx4 v[136:139], v[142:143], off offset:1024
	s_mov_b32 s0, 0x800000
	v_mov_b32_e32 v120, v13
	v_mov_b32_e32 v121, v14
	v_mov_b32_e32 v122, v12
	v_mov_b32_e32 v123, v15
	v_pk_add_f32 v[120:121], v[120:121], v[122:123]
	v_mov_b32_e32 v122, v8
	v_add_f32_e32 v120, v120, v121
	v_add_f32_e32 v40, 0, v120
	v_mov_b32_e32 v120, v9
	v_mov_b32_e32 v121, v10
	v_mov_b32_e32 v123, v11
	v_pk_add_f32 v[120:121], v[120:121], v[122:123]
	s_nop 0
	v_pk_add_f32 v[42:43], v[120:121], v[120:121] op_sel:[0,1] op_sel_hi:[1,0]
	v_add_f32_e32 v44, v4, v5
	v_add_f32_e32 v46, v6, v7
	v_mov_b32_e32 v41, v0
	v_mov_b32_e32 v43, v1
	v_mov_b32_e32 v45, v2
	v_mov_b32_e32 v47, v3
	v_pk_add_f32 v[40:41], v[40:41], v[42:43]
	v_pk_add_f32 v[42:43], v[44:45], v[46:47]
	s_nop 0
	v_pk_add_f32 v[40:41], v[40:41], v[42:43]
	s_nop 0
	v_add_f32_e32 v30, v40, v41
	ds_bpermute_b32 v39, v32, v30
	s_waitcnt lgkmcnt(0)
	v_add_f32_e32 v30, v30, v39
	ds_bpermute_b32 v39, v33, v30
	s_waitcnt lgkmcnt(0)
	v_add_f32_e32 v30, v30, v39
	ds_bpermute_b32 v39, v34, v30
	s_waitcnt lgkmcnt(0)
	v_add_f32_e32 v30, v30, v39
	ds_bpermute_b32 v39, v35, v30
	s_waitcnt lgkmcnt(0)
	v_add_f32_e32 v30, v30, v39
	ds_bpermute_b32 v39, v36, v30
	s_waitcnt lgkmcnt(0)
	v_add_f32_e32 v30, v30, v39
	ds_bpermute_b32 v39, v37, v30
	s_waitcnt lgkmcnt(0)
	v_add_f32_e32 v39, v30, v39
	v_fmamk_f32 v15, v39, 0xba800000, v15
	v_fmamk_f32 v14, v39, 0xba800000, v14
	v_fmamk_f32 v13, v39, 0xba800000, v13
	v_fmac_f32_e32 v12, 0xba800000, v39
	v_pk_mul_f32 v[40:41], v[14:15], v[14:15]
	v_pk_mul_f32 v[42:43], v[12:13], v[12:13]
	v_fmamk_f32 v11, v39, 0xba800000, v11
	v_pk_mov_b32 v[44:45], v[42:43], v[40:41] op_sel:[1,0]
	v_mov_b32_e32 v43, v41
	v_fmamk_f32 v10, v39, 0xba800000, v10
	v_fmamk_f32 v9, v39, 0xba800000, v9
	v_fmac_f32_e32 v8, 0xba800000, v39
	v_pk_add_f32 v[40:41], v[44:45], v[42:43]
	v_pk_mul_f32 v[42:43], v[10:11], v[10:11]
	v_pk_mul_f32 v[44:45], v[8:9], v[8:9]
	v_fmac_f32_e32 v4, 0xba800000, v39
	v_pk_mov_b32 v[46:47], v[44:45], v[42:43] op_sel:[1,0]
	v_mov_b32_e32 v45, v43
	v_fmamk_f32 v6, v39, 0xba800000, v6
	v_fmamk_f32 v5, v39, 0xba800000, v5
	v_mul_f32_e32 v30, v4, v4
	v_pk_add_f32 v[42:43], v[46:47], v[44:45]
	v_fmamk_f32 v7, v39, 0xba800000, v7
	v_pk_fma_f32 v[44:45], v[4:5], v[4:5], v[30:31] op_sel_hi:[1,1,0]
	v_mul_f32_e32 v30, v6, v6
	v_pk_add_f32 v[40:41], v[40:41], v[40:41] op_sel_hi:[0,1]
	v_pk_add_f32 v[42:43], v[42:43], v[42:43] op_sel_hi:[0,1]
	v_pk_fma_f32 v[46:47], v[6:7], v[6:7], v[30:31] op_sel_hi:[1,1,0]
	v_fmamk_f32 v3, v39, 0xba800000, v3
	v_fmamk_f32 v2, v39, 0xba800000, v2
	v_fmamk_f32 v1, v39, 0xba800000, v1
	v_fmac_f32_e32 v0, 0xba800000, v39
	v_mul_f32_e32 v44, v0, v0
	v_mul_f32_e32 v46, v1, v1
	v_mul_f32_e32 v40, v2, v2
	v_mul_f32_e32 v42, v3, v3
	v_pk_add_f32 v[44:45], v[44:45], v[46:47]
	v_pk_add_f32 v[40:41], v[40:41], v[42:43]
	s_nop 0
	v_pk_add_f32 v[40:41], v[44:45], v[40:41]
	s_nop 0
	v_add_f32_e32 v30, v40, v41
	ds_bpermute_b32 v40, v32, v30
	s_waitcnt lgkmcnt(0)
	v_add_f32_e32 v30, v30, v40
	ds_bpermute_b32 v40, v33, v30
	s_waitcnt lgkmcnt(0)
	v_add_f32_e32 v30, v30, v40
	ds_bpermute_b32 v40, v34, v30
	s_waitcnt lgkmcnt(0)
	v_add_f32_e32 v30, v30, v40
	ds_bpermute_b32 v40, v35, v30
	s_waitcnt lgkmcnt(0)
	v_add_f32_e32 v30, v30, v40
	ds_bpermute_b32 v40, v36, v30
	s_waitcnt lgkmcnt(0)
	v_add_f32_e32 v30, v30, v40
	ds_bpermute_b32 v40, v37, v30
	s_waitcnt lgkmcnt(0)
	v_add_f32_e32 v30, v30, v40
	v_fmamk_f32 v30, v30, 0x3a800000, v38
	v_cmp_gt_f32_e64 s[0:1], s0, v30
	v_mul_f32_e32 v40, 0x4b800000, v30
	s_nop 0
	v_cndmask_b32_e64 v30, v30, v40, s[0:1]
	v_rsq_f32_e32 v30, v30
	s_nop 0
	v_mul_f32_e32 v40, 0x45800000, v30
	v_cndmask_b32_e64 v30, v30, v40, s[0:1]
	s_and_saveexec_b64 s[0:1], vcc
	s_cbranch_execz .LBB0_1072
	v_mul_f32_e32 v40, 0x3a800000, v39
	v_mov_b32_e32 v41, v30
	global_store_dwordx2 v[24:25], v[40:41], off
	s_branch .LBB0_1072

; DI int tidx() { int t = __builtin_amdgcn_workitem_id_x(); asm volatile("" : "+v"(t)); return t; }
; DI void phase_ln(const Params& p, const float* g, const float* bta, const float* sh, const float* sc, bool writex, int bid, int nb) {
;   const int tid = tidx(), lane = tid & 63, wid = tid >> 6;
;   for (int row = bid * 8 + wid; row < NTOK; row += nb * 8) {
;     float* xr = p.out + (size_t)row * DM; const int b = row >> 12;
;     f32x4 v[4]; float s = 0.f;
; #pragma unroll
;     for (int e = 0; e < 4; ++e) { v[e] = *(const f32x4*)(xr + e * 256 + lane * 4); s += (v[e][0] + v[e][1]) + (v[e][2] + v[e][3]); }
; #pragma unroll
;     for (int o = 32; o > 0; o >>= 1) s += __shfl_xor(s, o);
;     const float mu = s * (1.f / 1024.f); float q = 0.f;
; #pragma unroll
;     for (int e = 0; e < 4; ++e) { v[e] -= mu; q += (v[e][0] * v[e][0] + v[e][1] * v[e][1]) + (v[e][2] * v[e][2] + v[e][3] * v[e][3]); }
; #pragma unroll
;     for (int o = 32; o > 0; o >>= 1) q += __shfl_xor(q, o);
;     const float rstd = rsqrtf(q * (1.f / 1024.f) + 1e-5f);
;     if (!writex && lane == 0) { f32x2 ms = {mu, rstd}; *(f32x2*)(p.lnstat + (size_t)row * 2) = ms; }
.LBB0_1828:
	s_or_b64 exec, exec, s[0:1]
	v_mov_b32_e32 v1, v206
	s_waitcnt lgkmcnt(0)
	s_barrier
	s_mov_b32 s0, 0x8000
	v_ashrrev_i32_e32 v0, 6, v1
	v_add_u32_e32 v43, s94, v0
	v_cmp_gt_i32_e32 vcc, s0, v43
	s_and_saveexec_b64 s[2:3], vcc
	s_cbranch_execz .LBB0_1833
	v_readlane_b32 s4, v252, 60
	v_readlane_b32 s12, v251, 4
	v_readlane_b32 s13, v251, 5
	v_readlane_b32 s14, v251, 6
	v_readlane_b32 s15, v251, 7
	v_readlane_b32 s16, v251, 8
	v_readlane_b32 s17, v251, 9
	v_readlane_b32 s18, v251, 10
	v_readlane_b32 s19, v251, 11
	s_mov_b64 s[12:13], s[16:17]
	v_readlane_b32 s6, v252, 62
	s_mov_b64 s[14:15], s[18:19]
	v_readlane_b32 s7, v252, 63
	s_add_u32 s6, s14, 0x1000
	v_readlane_b32 s8, v251, 0
	s_addc_u32 s7, s15, 0
	v_readlane_b32 s0, v251, 16
	v_readlane_b32 s9, v251, 1
	s_add_u32 s8, s12, 0x1000
	v_readlane_b32 s1, v251, 17
	s_addc_u32 s9, s13, 0
	s_lshl_b32 s4, s0, 3
	v_cmp_lt_i32_e64 s[0:1], v209, v208
	v_and_b32_e32 v6, 63, v1
	v_lshlrev_b32_e32 v2, 4, v6
	v_cndmask_b32_e64 v1, v207, v209, s[0:1]
	v_lshlrev_b32_e32 v44, 2, v1
	v_xor_b32_e32 v1, 16, v207
	v_cmp_lt_i32_e64 s[0:1], v1, v208
	v_mov_b32_e32 v3, 0
	v_or_b32_e32 v4, 0x400, v2
	v_cndmask_b32_e64 v1, v207, v1, s[0:1]
	v_lshlrev_b32_e32 v45, 2, v1
	v_xor_b32_e32 v1, 8, v207
	v_cmp_lt_i32_e64 s[0:1], v1, v208
	v_mov_b32_e32 v5, v3
	v_lshl_add_u64 v[20:21], s[8:9], 0, v[4:5]
	v_cndmask_b32_e64 v1, v207, v1, s[0:1]
	v_lshlrev_b32_e32 v46, 2, v1
	v_xor_b32_e32 v1, 4, v207
	v_cmp_lt_i32_e64 s[0:1], v1, v208
	v_lshl_add_u64 v[22:23], s[6:7], 0, v[4:5]
	v_or_b32_e32 v4, 0x800, v2
	v_cndmask_b32_e64 v1, v207, v1, s[0:1]
	v_lshlrev_b32_e32 v47, 2, v1
	v_xor_b32_e32 v1, 2, v207
	v_cmp_lt_i32_e64 s[0:1], v1, v208
	v_readlane_b32 s10, v251, 2
	v_readlane_b32 s11, v251, 3
	v_cndmask_b32_e64 v1, v207, v1, s[0:1]
	v_lshlrev_b32_e32 v48, 2, v1
	v_xor_b32_e32 v1, 1, v207
	v_lshl_add_u64 v[24:25], s[8:9], 0, v[4:5]
	v_lshl_add_u64 v[26:27], s[6:7], 0, v[4:5]
	v_or_b32_e32 v4, 0xc00, v2
	v_cmp_lt_i32_e64 s[0:1], v1, v208
	v_lshl_add_u64 v[16:17], s[8:9], 0, v[2:3]
	v_lshl_add_u64 v[28:29], s[8:9], 0, v[4:5]
	v_readlane_b32 s8, v252, 17
	v_cndmask_b32_e64 v1, v207, v1, s[0:1]
	v_readlane_b32 s9, v252, 18
	v_readlane_b32 s10, v252, 19
	v_readlane_b32 s11, v252, 20
	v_readlane_b32 s12, v252, 21
	v_readlane_b32 s13, v252, 22
	v_readlane_b32 s14, v252, 23
	v_readlane_b32 s15, v252, 24
	v_readlane_b32 s16, v252, 25
	v_readlane_b32 s17, v252, 26
	v_readlane_b32 s18, v252, 27
	v_readlane_b32 s19, v252, 28
	v_readlane_b32 s20, v252, 29
	v_readlane_b32 s21, v252, 30
	v_readlane_b32 s22, v252, 31
	v_readlane_b32 s23, v252, 32
	v_lshlrev_b32_e32 v49, 2, v1
	v_lshl_add_u64 v[30:31], s[6:7], 0, v[4:5]
	v_lshl_add_u64 v[4:5], s[16:17], 0, v[2:3]
	s_mov_b64 s[0:1], 0x34000
	v_ashrrev_i32_e32 v1, 31, v0
	s_ashr_i32 s95, s94, 31
	v_readlane_b32 s8, v252, 0
	v_lshl_add_u64 v[32:33], v[4:5], 0, s[0:1]
	s_mov_b64 s[0:1], 0x33000
	v_lshl_add_u64 v[0:1], v[0:1], 0, s[94:95]
	v_readlane_b32 s16, v252, 8
	v_readlane_b32 s17, v252, 9
	v_readlane_b32 s18, v252, 10
	v_readlane_b32 s19, v252, 11
	v_readlane_b32 s20, v252, 12
	v_readlane_b32 s21, v252, 13
	v_readlane_b32 s22, v252, 14
	v_readlane_b32 s23, v252, 15
	v_lshl_add_u64 v[34:35], v[4:5], 0, s[0:1]
	v_readlane_b32 s9, v252, 1
	v_lshlrev_b64 v[4:5], 12, v[0:1]
	v_readlane_b32 s16, v251, 19
	v_lshl_add_u64 v[36:37], v[0:1], 3, s[8:9]
	v_or_b32_e32 v4, v4, v2
	v_readlane_b32 s24, v251, 27
	v_readlane_b32 s25, v251, 28
	v_lshlrev_b64 v[0:1], 11, v[0:1]
	v_readlane_b32 s5, v252, 61
	v_lshl_add_u64 v[18:19], s[6:7], 0, v[2:3]
	v_readlane_b32 s14, v252, 6
	v_readlane_b32 s15, v252, 7
	v_lshl_add_u64 v[2:3], s[24:25], 0, v[4:5]
	s_mov_b64 s[0:1], 0x800
	v_lshl_or_b32 v0, v6, 3, v0
	v_readlane_b32 s10, v252, 2
	v_readlane_b32 s11, v252, 3
	v_readlane_b32 s12, v252, 4
	v_readlane_b32 s13, v252, 5
	s_ashr_i32 s5, s4, 31
	v_lshl_add_u64 v[38:39], v[2:3], 0, s[0:1]
	v_lshl_add_u64 v[0:1], s[14:15], 0, v[0:1]
	s_mov_b64 s[0:1], 0x400
	v_cmp_eq_u32_e32 vcc, 0, v6
	s_lshl_b64 s[6:7], s[4:5], 3
	s_lshl_b64 s[8:9], s[4:5], 12
	v_lshl_add_u64 v[40:41], v[0:1], 0, s[0:1]
	s_lshl_b64 s[10:11], s[4:5], 11
	s_mov_b64 s[12:13], 0
	v_mov_b32_e32 v50, 0x3727c5ac
	s_mov_b32 s5, 0x800000
	s_movk_i32 s14, 0x7fff
	v_readlane_b32 s17, v251, 20
	v_readlane_b32 s18, v251, 21
	v_readlane_b32 s19, v251, 22
	v_readlane_b32 s20, v251, 23
	v_readlane_b32 s21, v251, 24
	v_readlane_b32 s22, v251, 25
	v_readlane_b32 s23, v251, 26
	v_readlane_b32 s26, v251, 29
	v_readlane_b32 s27, v251, 30
	v_readlane_b32 s28, v251, 31
	v_readlane_b32 s29, v251, 32
	v_readlane_b32 s30, v251, 33
	v_readlane_b32 s31, v251, 34
	global_load_dwordx4 v[72:75], v[16:17], off
	global_load_dwordx4 v[88:91], v[18:19], off
	global_load_dwordx4 v[76:79], v[20:21], off
	global_load_dwordx4 v[92:95], v[22:23], off
	global_load_dwordx4 v[80:83], v[24:25], off
	global_load_dwordx4 v[96:99], v[26:27], off
	global_load_dwordx4 v[84:87], v[28:29], off
	global_load_dwordx4 v[100:103], v[30:31], off
	s_mov_b32 s101, -1
	global_load_dwordx4 v[136:139], v[38:39], off offset:-2048
	global_load_dwordx4 v[140:143], v[38:39], off offset:-1024
	global_load_dwordx4 v[144:147], v[38:39], off
	global_load_dwordx4 v[148:151], v[38:39], off offset:1024
	s_waitcnt vmcnt(0)
	s_branch .LBB0_1831

; DI void st4(bf16_t* p, float a, float b, float c, float d) { u32x2 w = {pk2(a, b), pk2(c, d)}; *(u32x2*)p = w; }
; DI void phase_ln(const Params& p, const float* g, const float* bta, const float* sh, const float* sc, bool writex, int bid, int nb) {
;     ...
;   for (int row = bid * 8 + wid; row < NTOK; row += nb * 8) {
;     float* xr = p.out + (size_t)row * DM; const int b = row >> 12;
;     f32x4 v[4]; float s = 0.f;
; #pragma unroll
;     for (int e = 0; e < 4; ++e) { v[e] = *(const f32x4*)(xr + e * 256 + lane * 4); s += (v[e][0] + v[e][1]) + (v[e][2] + v[e][3]); }
; #pragma unroll
;     for (int o = 32; o > 0; o >>= 1) s += __shfl_xor(s, o);
;     const float mu = s * (1.f / 1024.f); float q = 0.f;
; #pragma unroll
;     for (int e = 0; e < 4; ++e) { v[e] -= mu; q += (v[e][0] * v[e][0] + v[e][1] * v[e][1]) + (v[e][2] * v[e][2] + v[e][3] * v[e][3]); }
; #pragma unroll
;     for (int o = 32; o > 0; o >>= 1) q += __shfl_xor(q, o);
;     const float rstd = rsqrtf(q * (1.f / 1024.f) + 1e-5f);
;     if (!writex && lane == 0) { f32x2 ms = {mu, rstd}; *(f32x2*)(p.lnstat + (size_t)row * 2) = ms; }
; #pragma unroll
;     for (int e = 0; e < 4; ++e) { const int col = e * 256 + lane * 4;
;       const f32x4 y = v[e] * rstd * *(const f32x4*)(g + col) + *(const f32x4*)(bta + col);
;       if (writex) *(f32x4*)(xr + col) = y;
;       if (sh) { const f32x4 hv = y * (*(const f32x4*)(sc + b * 6144 + col) + 1.f) + *(const f32x4*)(sh + b * 6144 + col); st4(p.H + (size_t)row * DM + col, hv[0], hv[1], hv[2], hv[3]); } }
.LBB0_1831:
	s_waitcnt vmcnt(5)
	v_ashrrev_i32_e32 v156, 12, v43
	v_mov_b64_e32 v[12:13], v[136:137]
	v_mov_b64_e32 v[14:15], v[138:139]
	v_mov_b64_e32 v[8:9], v[140:141]
	v_mov_b64_e32 v[10:11], v[142:143]
	v_mov_b64_e32 v[4:5], v[144:145]
	v_mov_b64_e32 v[6:7], v[146:147]
	v_mov_b64_e32 v[0:1], v[148:149]
	v_mov_b64_e32 v[2:3], v[150:151]
	v_readfirstlane_b32 s100, v156
	s_nop 3
	s_cmp_eq_u32 s100, s101
	s_cbranch_scc1 .Lln_skip_c
	s_mov_b32 s101, s100
	v_mul_i32_i24_e32 v156, 0x1800, v156
	v_ashrrev_i32_e32 v157, 31, v156
	v_lshlrev_b64 v[156:157], 2, v[156:157]
	v_lshl_add_u64 v[158:159], v[32:33], 0, v[156:157]
	v_lshl_add_u64 v[156:157], v[34:35], 0, v[156:157]
	global_load_dwordx4 v[104:107], v[158:159], off
	global_load_dwordx4 v[120:123], v[156:157], off
	global_load_dwordx4 v[108:111], v[158:159], off offset:1024
	global_load_dwordx4 v[124:127], v[156:157], off offset:1024
	global_load_dwordx4 v[112:115], v[158:159], off offset:2048
	global_load_dwordx4 v[128:131], v[156:157], off offset:2048
	global_load_dwordx4 v[116:119], v[158:159], off offset:3072
	global_load_dwordx4 v[132:135], v[156:157], off offset:3072
.Lln_skip_c:
	v_add_u32_e32 v160, s4, v43
	v_cmp_ge_i32_e64 s[98:99], s14, v160
	v_lshl_add_u64 v[162:163], v[38:39], 0, s[8:9]
	s_nop 1
	v_cndmask_b32_e64 v162, v38, v162, s[98:99]
	v_cndmask_b32_e64 v163, v39, v163, s[98:99]
	global_load_dwordx4 v[136:139], v[162:163], off offset:-2048
	global_load_dwordx4 v[140:143], v[162:163], off offset:-1024
	global_load_dwordx4 v[144:147], v[162:163], off
	global_load_dwordx4 v[148:151], v[162:163], off offset:1024
	v_mov_b32_e32 v52, v13
	v_mov_b32_e32 v53, v14
	v_mov_b32_e32 v54, v12
	v_mov_b32_e32 v55, v15
	v_mov_b32_e32 v56, v9
	v_mov_b32_e32 v57, v10
	v_mov_b32_e32 v58, v8
	v_mov_b32_e32 v59, v11
	v_pk_add_f32 v[52:53], v[52:53], v[54:55]
	v_pk_add_f32 v[54:55], v[56:57], v[58:59]
	v_add_f32_e32 v42, v52, v53
	v_pk_add_f32 v[52:53], v[54:55], v[54:55] op_sel:[0,1] op_sel_hi:[1,0]
	v_add_f32_e32 v60, v4, v5
	v_add_f32_e32 v62, v6, v7
	v_mov_b32_e32 v65, v0
	v_mov_b32_e32 v61, v2
	v_mov_b32_e32 v63, v3
	v_add_f32_e32 v64, 0, v42
	v_mov_b32_e32 v53, v1
	v_pk_add_f32 v[56:57], v[60:61], v[62:63]
	v_pk_add_f32 v[52:53], v[64:65], v[52:53]
	s_nop 0
	v_pk_add_f32 v[52:53], v[52:53], v[56:57]
	s_nop 0
	v_add_f32_e32 v42, v52, v53
	ds_bpermute_b32 v51, v44, v42
	s_waitcnt lgkmcnt(0)
	v_add_f32_e32 v42, v42, v51
	ds_bpermute_b32 v51, v45, v42
	s_waitcnt lgkmcnt(0)
	v_add_f32_e32 v42, v42, v51
	ds_bpermute_b32 v51, v46, v42
	s_waitcnt lgkmcnt(0)
	v_add_f32_e32 v42, v42, v51
	ds_bpermute_b32 v51, v47, v42
	s_waitcnt lgkmcnt(0)
	v_add_f32_e32 v42, v42, v51
	ds_bpermute_b32 v51, v48, v42
	s_waitcnt lgkmcnt(0)
	v_add_f32_e32 v42, v42, v51
	ds_bpermute_b32 v51, v49, v42
	s_waitcnt lgkmcnt(0)
	v_add_f32_e32 v51, v42, v51
	v_fmamk_f32 v15, v51, 0xba800000, v15
	v_fmamk_f32 v14, v51, 0xba800000, v14
	v_fmamk_f32 v13, v51, 0xba800000, v13
	v_fmac_f32_e32 v12, 0xba800000, v51
	v_fmamk_f32 v11, v51, 0xba800000, v11
	v_fmamk_f32 v10, v51, 0xba800000, v10
	v_fmamk_f32 v9, v51, 0xba800000, v9
	v_fmac_f32_e32 v8, 0xba800000, v51
	v_pk_mul_f32 v[52:53], v[14:15], v[14:15]
	v_pk_mul_f32 v[54:55], v[12:13], v[12:13]
	v_pk_mul_f32 v[56:57], v[10:11], v[10:11]
	v_pk_mul_f32 v[58:59], v[8:9], v[8:9]
	v_fmamk_f32 v6, v51, 0xba800000, v6
	v_fmac_f32_e32 v4, 0xba800000, v51
	v_pk_mov_b32 v[62:63], v[54:55], v[52:53] op_sel:[1,0]
	v_mov_b32_e32 v55, v53
	v_pk_mov_b32 v[52:53], v[58:59], v[56:57] op_sel:[1,0]
	v_mov_b32_e32 v59, v57
	v_fmamk_f32 v7, v51, 0xba800000, v7
	v_fmamk_f32 v5, v51, 0xba800000, v5
	v_mul_f32_e32 v42, v4, v4
	v_mul_f32_e32 v60, v6, v6
	v_pk_add_f32 v[54:55], v[62:63], v[54:55]
	v_pk_add_f32 v[52:53], v[52:53], v[58:59]
	v_fmamk_f32 v3, v51, 0xba800000, v3
	v_fmamk_f32 v2, v51, 0xba800000, v2
	v_fmamk_f32 v1, v51, 0xba800000, v1
	v_fmac_f32_e32 v0, 0xba800000, v51
	v_pk_fma_f32 v[56:57], v[4:5], v[4:5], v[42:43] op_sel_hi:[1,1,0]
	v_pk_fma_f32 v[60:61], v[6:7], v[6:7], v[60:61] op_sel_hi:[1,1,0]
	v_pk_add_f32 v[54:55], v[54:55], v[54:55] op_sel_hi:[0,1]
	v_pk_add_f32 v[52:53], v[52:53], v[52:53] op_sel_hi:[0,1]
	v_mul_f32_e32 v56, v0, v0
	v_mul_f32_e32 v60, v1, v1
	v_mul_f32_e32 v54, v2, v2
	v_mul_f32_e32 v52, v3, v3
	v_pk_add_f32 v[56:57], v[56:57], v[60:61]
	v_pk_add_f32 v[52:53], v[54:55], v[52:53]
	s_nop 0
	v_pk_add_f32 v[52:53], v[56:57], v[52:53]
	s_nop 0
	v_add_f32_e32 v42, v52, v53
	ds_bpermute_b32 v52, v44, v42
	s_waitcnt lgkmcnt(0)
	v_add_f32_e32 v42, v42, v52
	ds_bpermute_b32 v52, v45, v42
	s_waitcnt lgkmcnt(0)
	v_add_f32_e32 v42, v42, v52
	ds_bpermute_b32 v52, v46, v42
	s_waitcnt lgkmcnt(0)
	v_add_f32_e32 v42, v42, v52
	ds_bpermute_b32 v52, v47, v42
	s_waitcnt lgkmcnt(0)
	v_add_f32_e32 v42, v42, v52
	ds_bpermute_b32 v52, v48, v42
	s_waitcnt lgkmcnt(0)
	v_add_f32_e32 v42, v42, v52
	ds_bpermute_b32 v52, v49, v42
	s_waitcnt lgkmcnt(0)
	v_add_f32_e32 v42, v42, v52
	v_fmamk_f32 v42, v42, 0x3a800000, v50
	v_mul_f32_e32 v52, 0x4b800000, v42
	v_cmp_gt_f32_e64 s[0:1], s5, v42
	s_nop 1
	v_cndmask_b32_e64 v42, v42, v52, s[0:1]
	v_rsq_f32_e32 v42, v42
	s_nop 0
	v_mul_f32_e32 v52, 0x45800000, v42
	v_cndmask_b32_e64 v42, v42, v52, s[0:1]
	s_and_saveexec_b64 s[0:1], vcc
	s_cbranch_execz .LBB0_1830
	v_mul_f32_e32 v52, 0x3a800000, v51
	v_mov_b32_e32 v53, v42
	global_store_dwordx2 v[36:37], v[52:53], off
	s_branch .LBB0_1830
